# first grid barrier (phase 0 -> layer-0 RMSNorm) replaced by a modulation-ready counter published by the 96 producer workgroups
# baseline (speedup 1.0000x reference)
.LBB0_88:
	s_waitcnt vmcnt(0)
	s_barrier
	s_cmp_lt_u32 s52, 0x60
	s_cbranch_scc0 .Lm0_nopub
	s_and_saveexec_b64 s[0:1], s[54:55]
	s_cbranch_execz .Lm0_pubj
	buffer_wbl2 sc1
	s_waitcnt vmcnt(0)
	v_readlane_b32 s4, v253, 24
	v_readlane_b32 s5, v253, 25
	v_mov_b32_e32 v0, 1
	v_mov_b32_e32 v1, 0x180
	s_nop 4
	global_atomic_add v1, v0, s[4:5]
.Lm0_pubj:
	s_or_b64 exec, exec, s[0:1]
.Lm0_nopub:
	s_lshl_b32 s56, s52, 9
	s_waitcnt vmcnt(2)
	v_add_u32_e32 v0, s56, v48
	s_mov_b32 s0, 0x20000
	v_cmp_gt_i32_e32 vcc, s0, v0
	s_and_saveexec_b64 s[0:1], vcc
	s_cbranch_execz .LBB0_119
	s_add_u32 s4, s6, 0x109c0000
	s_mov_b32 s10, 0x6dc9c883
	s_mov_b32 s12, 0x54442d18
	s_mov_b32 s14, 0x33145c07
	s_mov_b32 s16, 0x67f544e4
	s_waitcnt vmcnt(1)
	v_mov_b32_e32 v4, 0x1a01a01a
	v_mov_b32_e32 v8, 0x55555555
	s_mov_b32 s18, 0xeff8d898
	s_addc_u32 s5, s7, 0
	s_lshl_b32 s3, s98, 9
	v_and_b32_e32 v24, 7, v48
	s_mov_b64 s[8:9], 0
	s_mov_b32 s11, 0x3fe45f30
	s_mov_b32 s13, 0xbff921fb
	s_mov_b32 s15, 0xbc91a626
	v_mov_b32_e32 v2, 0xa556c734
	v_mov_b32_e32 v3, 0x3ec71de3
	s_mov_b32 s17, 0xbe5ae645
	v_mov_b32_e32 v5, 0xbf2a01a0
	v_mov_b32_e32 v6, 0x11111111
	v_mov_b32_e32 v7, 0x3f811111
	v_mov_b32_e32 v9, 0xbfc55555
	v_mov_b32_e32 v10, 0xb7789f5c
	v_mov_b32_e32 v11, 0xbe927e4f
	s_mov_b32 s19, 0x3e21eed8
	v_mov_b32_e32 v13, 0x3efa01a0
	v_mov_b32_e32 v12, v4
	v_mov_b32_e32 v14, 0x16c16c17
	v_mov_b32_e32 v15, 0xbf56c16c
	v_mov_b32_e32 v17, 0x3fa55555
	v_mov_b32_e32 v16, v8
	s_mov_b32 s26, 0x1ffff
	s_branch .LBB0_92

.LBB0_123:
	s_or_b64 exec, exec, s[0:1]
	s_waitcnt vmcnt(0)
	s_barrier
	s_and_saveexec_b64 s[0:1], s[54:55]
	s_cbranch_execz .LBB0_175
	v_readlane_b32 s4, v253, 24
	v_readlane_b32 s5, v253, 25
	s_mov_b32 s3, 0
	v_mov_b32_e32 v1, 0
	s_nop 4
.Lm0_spin:
	global_load_dword v0, v1, s[4:5] offset:384 sc1
	s_waitcnt vmcnt(0)
	v_readfirstlane_b32 s6, v0
	s_nop 3
	s_cmpk_ge_u32 s6, 0x60
	s_cbranch_scc1 .Lm0_done
	s_sleep 1
	s_add_i32 s3, s3, 1
	s_cmp_lt_u32 s3, 0x100000
	s_cbranch_scc1 .Lm0_spin
.Lm0_done:
	buffer_inv sc1
	s_waitcnt vmcnt(0)

.LBB0_241:
	s_or_b64 exec, exec, s[0:1]
	v_readlane_b32 s4, v253, 24
	v_readlane_b32 s5, v253, 25
	v_mov_b32_e32 v254, 0
	s_nop 4
	global_load_dword v254, v254, s[4:5] sc1
	s_waitcnt vmcnt(0)
	v_readlane_b32 s2, v253, 26
	v_readlane_b32 s3, v253, 27
	s_mov_b64 s[0:1], 0
	s_andn2_b64 vcc, exec, s[2:3]
	s_waitcnt lgkmcnt(0)
	s_barrier
	s_cbranch_vccnz .LBB0_243
	v_lshrrev_b32_e32 v120, 4, v197
	v_and_b32_e32 v121, 15, v197
	v_lshlrev_b32_e32 v121, 2, v121
	v_lshl_add_u32 v122, v120, 10, v121
	v_lshlrev_b32_e32 v122, 2, v122
	v_mul_u32_u24_e32 v138, 0x8800, v120
	v_lshl_add_u32 v138, v121, 2, v138
	v_mul_u32_u24_e32 v123, 0x41, v120
	v_add_u32_e32 v123, v123, v121
	v_lshlrev_b32_e32 v123, 2, v123
	v_lshrrev_b32_e32 v124, 3, v197
	v_and_b32_e32 v125, 7, v197
	v_lshlrev_b32_e32 v125, 3, v125
	v_bfe_u32 v127, v124, 2, 2
	v_lshlrev_b32_e32 v127, 3, v127
	v_bfe_u32 v136, v124, 4, 1
	v_lshl_add_u32 v127, v136, 2, v127
	v_and_b32_e32 v136, 3, v124
	v_add_u32_e32 v127, v127, v136
	v_and_b32_e32 v136, 32, v124
	v_add_u32_e32 v127, v127, v136
	v_mul_u32_u24_e32 v136, 0x41, v125
	v_add_u32_e32 v136, v136, v127
	v_lshlrev_b32_e32 v136, 2, v136
	v_lshl_add_u32 v137, v124, 10, v125
	v_lshlrev_b32_e32 v137, 1, v137
	s_sub_i32 s2, s52, 0x80
	v_readlane_b32 s3, v252, 23
	s_nop 3
	s_cmp_eq_u32 s3, 0
	s_cbranch_scc1 .Lcw_l1
	v_readlane_b32 s28, v253, 4
	v_readlane_b32 s29, v253, 5
	v_readlane_b32 s30, v253, 6
	v_readlane_b32 s31, v253, 7
	s_nop 3
	s_add_i32 s4, s2, 0
	s_cmpk_lt_u32 s4, 0x200
	s_cselect_b32 s6, s28, s30
	s_cselect_b32 s7, s29, s31
	s_mov_b32 s16, 0x10500000
	s_cselect_b32 s16, 0x10100000, s16
	s_bfe_u32 s5, s4, 0x10008
	s_lshl_b32 s3, s5, 22
	s_add_u32 s6, s6, s3
	s_addc_u32 s7, s7, 0
	s_lshl_b32 s3, s5, 21
	s_add_i32 s16, s16, s3
	s_and_b32 s3, s4, 15
	s_bfe_u32 s5, s4, 0x40004
	s_lshl_b32 s17, s3, 18
	s_lshl_b32 s20, s5, 8
	s_add_i32 s17, s17, s20
	s_add_u32 s6, s6, s17
	s_addc_u32 s7, s7, 0
	s_add_u32 s12, s6, 0x20000
	s_addc_u32 s13, s7, 0
	s_lshl_b32 s17, s5, 17
	s_lshl_b32 s20, s3, 7
	s_add_i32 s17, s17, s20
	s_add_i32 s16, s16, s17
	s_add_u32 s16, s96, s16
	s_addc_u32 s17, s97, 0
	global_load_dwordx4 v[140:143], v122, s[6:7]
	global_load_dwordx4 v[150:153], v122, s[12:13]
	s_waitcnt vmcnt(0)
	ds_write_b32 v123, v140 offset:0
	ds_write_b32 v123, v141 offset:4
	ds_write_b32 v123, v142 offset:8
	ds_write_b32 v123, v143 offset:12
	ds_write_b32 v123, v150 offset:8320
	ds_write_b32 v123, v151 offset:8324
	ds_write_b32 v123, v152 offset:8328
	ds_write_b32 v123, v153 offset:8332
	s_waitcnt lgkmcnt(0)
	s_barrier
	s_mov_b64 s[26:27], s[16:17]
	s_add_i32 s4, s2, 128
	s_cmpk_lt_u32 s4, 0x200
	s_cselect_b32 s6, s28, s30
	s_cselect_b32 s7, s29, s31
	s_mov_b32 s16, 0x10500000
	s_cselect_b32 s16, 0x10100000, s16
	s_bfe_u32 s5, s4, 0x10008
	s_lshl_b32 s3, s5, 22
	s_add_u32 s6, s6, s3
	s_addc_u32 s7, s7, 0
	s_lshl_b32 s3, s5, 21
	s_add_i32 s16, s16, s3
	s_and_b32 s3, s4, 15
	s_bfe_u32 s5, s4, 0x40004
	s_lshl_b32 s17, s3, 18
	s_lshl_b32 s20, s5, 8
	s_add_i32 s17, s17, s20
	s_add_u32 s6, s6, s17
	s_addc_u32 s7, s7, 0
	s_add_u32 s12, s6, 0x20000
	s_addc_u32 s13, s7, 0
	s_lshl_b32 s17, s5, 17
	s_lshl_b32 s20, s3, 7
	s_add_i32 s17, s17, s20
	s_add_i32 s16, s16, s17
	s_add_u32 s16, s96, s16
	s_addc_u32 s17, s97, 0
	global_load_dwordx4 v[140:143], v122, s[6:7]
	global_load_dwordx4 v[150:153], v122, s[12:13]
	ds_read_b32 v154, v136 offset:0
	ds_read_b32 v155, v136 offset:260
	ds_read_b32 v156, v136 offset:520
	ds_read_b32 v157, v136 offset:780
	ds_read_b32 v158, v136 offset:1040
	ds_read_b32 v159, v136 offset:1300
	ds_read_b32 v160, v136 offset:1560
	ds_read_b32 v161, v136 offset:1820
	s_waitcnt lgkmcnt(0)
	v_cvt_pk_bf16_f32 v204, v154, v155
	v_cvt_pk_bf16_f32 v205, v156, v157
	v_cvt_pk_bf16_f32 v206, v158, v159
	v_cvt_pk_bf16_f32 v207, v160, v161
	global_store_dwordx4 v137, v[204:207], s[26:27]
	s_barrier
	s_waitcnt vmcnt(0)
	ds_write_b32 v123, v140 offset:0
	ds_write_b32 v123, v141 offset:4
	ds_write_b32 v123, v142 offset:8
	ds_write_b32 v123, v143 offset:12
	ds_write_b32 v123, v150 offset:8320
	ds_write_b32 v123, v151 offset:8324
	ds_write_b32 v123, v152 offset:8328
	ds_write_b32 v123, v153 offset:8332
	s_waitcnt lgkmcnt(0)
	s_barrier
	s_mov_b64 s[26:27], s[16:17]
	s_add_i32 s4, s2, 256
	s_cmpk_lt_u32 s4, 0x200
	s_cselect_b32 s6, s28, s30
	s_cselect_b32 s7, s29, s31
	s_mov_b32 s16, 0x10500000
	s_cselect_b32 s16, 0x10100000, s16
	s_bfe_u32 s5, s4, 0x10008
	s_lshl_b32 s3, s5, 22
	s_add_u32 s6, s6, s3
	s_addc_u32 s7, s7, 0
	s_lshl_b32 s3, s5, 21
	s_add_i32 s16, s16, s3
	s_and_b32 s3, s4, 15
	s_bfe_u32 s5, s4, 0x40004
	s_lshl_b32 s17, s3, 18
	s_lshl_b32 s20, s5, 8
	s_add_i32 s17, s17, s20
	s_add_u32 s6, s6, s17
	s_addc_u32 s7, s7, 0
	s_add_u32 s12, s6, 0x20000
	s_addc_u32 s13, s7, 0
	s_lshl_b32 s17, s5, 17
	s_lshl_b32 s20, s3, 7
	s_add_i32 s17, s17, s20
	s_add_i32 s16, s16, s17
	s_add_u32 s16, s96, s16
	s_addc_u32 s17, s97, 0
	global_load_dwordx4 v[140:143], v122, s[6:7]
	global_load_dwordx4 v[150:153], v122, s[12:13]
	ds_read_b32 v154, v136 offset:0
	ds_read_b32 v155, v136 offset:260
	ds_read_b32 v156, v136 offset:520
	ds_read_b32 v157, v136 offset:780
	ds_read_b32 v158, v136 offset:1040
	ds_read_b32 v159, v136 offset:1300
	ds_read_b32 v160, v136 offset:1560
	ds_read_b32 v161, v136 offset:1820
	s_waitcnt lgkmcnt(0)
	v_cvt_pk_bf16_f32 v204, v154, v155
	v_cvt_pk_bf16_f32 v205, v156, v157
	v_cvt_pk_bf16_f32 v206, v158, v159
	v_cvt_pk_bf16_f32 v207, v160, v161
	global_store_dwordx4 v137, v[204:207], s[26:27]
	s_barrier
	s_waitcnt vmcnt(0)
	ds_write_b32 v123, v140 offset:0
	ds_write_b32 v123, v141 offset:4
	ds_write_b32 v123, v142 offset:8
	ds_write_b32 v123, v143 offset:12
	ds_write_b32 v123, v150 offset:8320
	ds_write_b32 v123, v151 offset:8324
	ds_write_b32 v123, v152 offset:8328
	ds_write_b32 v123, v153 offset:8332
	s_waitcnt lgkmcnt(0)
	s_barrier
	s_mov_b64 s[26:27], s[16:17]
	s_add_i32 s4, s2, 384
	s_cmpk_lt_u32 s4, 0x200
	s_cselect_b32 s6, s28, s30
	s_cselect_b32 s7, s29, s31
	s_mov_b32 s16, 0x10500000
	s_cselect_b32 s16, 0x10100000, s16
	s_bfe_u32 s5, s4, 0x10008
	s_lshl_b32 s3, s5, 22
	s_add_u32 s6, s6, s3
	s_addc_u32 s7, s7, 0
	s_lshl_b32 s3, s5, 21
	s_add_i32 s16, s16, s3
	s_and_b32 s3, s4, 15
	s_bfe_u32 s5, s4, 0x40004
	s_lshl_b32 s17, s3, 18
	s_lshl_b32 s20, s5, 8
	s_add_i32 s17, s17, s20
	s_add_u32 s6, s6, s17
	s_addc_u32 s7, s7, 0
	s_add_u32 s12, s6, 0x20000
	s_addc_u32 s13, s7, 0
	s_lshl_b32 s17, s5, 17
	s_lshl_b32 s20, s3, 7
	s_add_i32 s17, s17, s20
	s_add_i32 s16, s16, s17
	s_add_u32 s16, s96, s16
	s_addc_u32 s17, s97, 0
	global_load_dwordx4 v[140:143], v122, s[6:7]
	global_load_dwordx4 v[150:153], v122, s[12:13]
	ds_read_b32 v154, v136 offset:0
	ds_read_b32 v155, v136 offset:260
	ds_read_b32 v156, v136 offset:520
	ds_read_b32 v157, v136 offset:780
	ds_read_b32 v158, v136 offset:1040
	ds_read_b32 v159, v136 offset:1300
	ds_read_b32 v160, v136 offset:1560
	ds_read_b32 v161, v136 offset:1820
	s_waitcnt lgkmcnt(0)
	v_cvt_pk_bf16_f32 v204, v154, v155
	v_cvt_pk_bf16_f32 v205, v156, v157
	v_cvt_pk_bf16_f32 v206, v158, v159
	v_cvt_pk_bf16_f32 v207, v160, v161
	global_store_dwordx4 v137, v[204:207], s[26:27]
	s_barrier
	s_waitcnt vmcnt(0)
	ds_write_b32 v123, v140 offset:0
	ds_write_b32 v123, v141 offset:4
	ds_write_b32 v123, v142 offset:8
	ds_write_b32 v123, v143 offset:12
	ds_write_b32 v123, v150 offset:8320
	ds_write_b32 v123, v151 offset:8324
	ds_write_b32 v123, v152 offset:8328
	ds_write_b32 v123, v153 offset:8332
	s_waitcnt lgkmcnt(0)
	s_barrier
	s_mov_b64 s[26:27], s[16:17]
	s_add_i32 s4, s2, 512
	s_cmpk_lt_u32 s4, 0x200
	s_cselect_b32 s6, s28, s30
	s_cselect_b32 s7, s29, s31
	s_mov_b32 s16, 0x10500000
	s_cselect_b32 s16, 0x10100000, s16
	s_bfe_u32 s5, s4, 0x10008
	s_lshl_b32 s3, s5, 22
	s_add_u32 s6, s6, s3
	s_addc_u32 s7, s7, 0
	s_lshl_b32 s3, s5, 21
	s_add_i32 s16, s16, s3
	s_and_b32 s3, s4, 15
	s_bfe_u32 s5, s4, 0x40004
	s_lshl_b32 s17, s3, 18
	s_lshl_b32 s20, s5, 8
	s_add_i32 s17, s17, s20
	s_add_u32 s6, s6, s17
	s_addc_u32 s7, s7, 0
	s_add_u32 s12, s6, 0x20000
	s_addc_u32 s13, s7, 0
	s_lshl_b32 s17, s5, 17
	s_lshl_b32 s20, s3, 7
	s_add_i32 s17, s17, s20
	s_add_i32 s16, s16, s17
	s_add_u32 s16, s96, s16
	s_addc_u32 s17, s97, 0
	global_load_dwordx4 v[140:143], v122, s[6:7]
	global_load_dwordx4 v[150:153], v122, s[12:13]
	ds_read_b32 v154, v136 offset:0
	ds_read_b32 v155, v136 offset:260
	ds_read_b32 v156, v136 offset:520
	ds_read_b32 v157, v136 offset:780
	ds_read_b32 v158, v136 offset:1040
	ds_read_b32 v159, v136 offset:1300
	ds_read_b32 v160, v136 offset:1560
	ds_read_b32 v161, v136 offset:1820
	s_waitcnt lgkmcnt(0)
	v_cvt_pk_bf16_f32 v204, v154, v155
	v_cvt_pk_bf16_f32 v205, v156, v157
	v_cvt_pk_bf16_f32 v206, v158, v159
	v_cvt_pk_bf16_f32 v207, v160, v161
	global_store_dwordx4 v137, v[204:207], s[26:27]
	s_barrier
	s_waitcnt vmcnt(0)
	ds_write_b32 v123, v140 offset:0
	ds_write_b32 v123, v141 offset:4
	ds_write_b32 v123, v142 offset:8
	ds_write_b32 v123, v143 offset:12
	ds_write_b32 v123, v150 offset:8320
	ds_write_b32 v123, v151 offset:8324
	ds_write_b32 v123, v152 offset:8328
	ds_write_b32 v123, v153 offset:8332
	s_waitcnt lgkmcnt(0)
	s_barrier
	s_mov_b64 s[26:27], s[16:17]
	s_add_i32 s4, s2, 640
	s_cmpk_lt_u32 s4, 0x200
	s_cselect_b32 s6, s28, s30
	s_cselect_b32 s7, s29, s31
	s_mov_b32 s16, 0x10500000
	s_cselect_b32 s16, 0x10100000, s16
	s_bfe_u32 s5, s4, 0x10008
	s_lshl_b32 s3, s5, 22
	s_add_u32 s6, s6, s3
	s_addc_u32 s7, s7, 0
	s_lshl_b32 s3, s5, 21
	s_add_i32 s16, s16, s3
	s_and_b32 s3, s4, 15
	s_bfe_u32 s5, s4, 0x40004
	s_lshl_b32 s17, s3, 18
	s_lshl_b32 s20, s5, 8
	s_add_i32 s17, s17, s20
	s_add_u32 s6, s6, s17
	s_addc_u32 s7, s7, 0
	s_add_u32 s12, s6, 0x20000
	s_addc_u32 s13, s7, 0
	s_lshl_b32 s17, s5, 17
	s_lshl_b32 s20, s3, 7
	s_add_i32 s17, s17, s20
	s_add_i32 s16, s16, s17
	s_add_u32 s16, s96, s16
	s_addc_u32 s17, s97, 0
	global_load_dwordx4 v[140:143], v122, s[6:7]
	global_load_dwordx4 v[150:153], v122, s[12:13]
	ds_read_b32 v154, v136 offset:0
	ds_read_b32 v155, v136 offset:260
	ds_read_b32 v156, v136 offset:520
	ds_read_b32 v157, v136 offset:780
	ds_read_b32 v158, v136 offset:1040
	ds_read_b32 v159, v136 offset:1300
	ds_read_b32 v160, v136 offset:1560
	ds_read_b32 v161, v136 offset:1820
	s_waitcnt lgkmcnt(0)
	v_cvt_pk_bf16_f32 v204, v154, v155
	v_cvt_pk_bf16_f32 v205, v156, v157
	v_cvt_pk_bf16_f32 v206, v158, v159
	v_cvt_pk_bf16_f32 v207, v160, v161
	global_store_dwordx4 v137, v[204:207], s[26:27]
	s_barrier
	s_waitcnt vmcnt(0)
	ds_write_b32 v123, v140 offset:0
	ds_write_b32 v123, v141 offset:4
	ds_write_b32 v123, v142 offset:8
	ds_write_b32 v123, v143 offset:12
	ds_write_b32 v123, v150 offset:8320
	ds_write_b32 v123, v151 offset:8324
	ds_write_b32 v123, v152 offset:8328
	ds_write_b32 v123, v153 offset:8332
	s_waitcnt lgkmcnt(0)
	s_barrier
	s_mov_b64 s[26:27], s[16:17]
	s_add_i32 s4, s2, 768
	s_cmpk_lt_u32 s4, 0x200
	s_cselect_b32 s6, s28, s30
	s_cselect_b32 s7, s29, s31
	s_mov_b32 s16, 0x10500000
	s_cselect_b32 s16, 0x10100000, s16
	s_bfe_u32 s5, s4, 0x10008
	s_lshl_b32 s3, s5, 22
	s_add_u32 s6, s6, s3
	s_addc_u32 s7, s7, 0
	s_lshl_b32 s3, s5, 21
	s_add_i32 s16, s16, s3
	s_and_b32 s3, s4, 15
	s_bfe_u32 s5, s4, 0x40004
	s_lshl_b32 s17, s3, 18
	s_lshl_b32 s20, s5, 8
	s_add_i32 s17, s17, s20
	s_add_u32 s6, s6, s17
	s_addc_u32 s7, s7, 0
	s_add_u32 s12, s6, 0x20000
	s_addc_u32 s13, s7, 0
	s_lshl_b32 s17, s5, 17
	s_lshl_b32 s20, s3, 7
	s_add_i32 s17, s17, s20
	s_add_i32 s16, s16, s17
	s_add_u32 s16, s96, s16
	s_addc_u32 s17, s97, 0
	global_load_dwordx4 v[140:143], v122, s[6:7]
	global_load_dwordx4 v[150:153], v122, s[12:13]
	ds_read_b32 v154, v136 offset:0
	ds_read_b32 v155, v136 offset:260
	ds_read_b32 v156, v136 offset:520
	ds_read_b32 v157, v136 offset:780
	ds_read_b32 v158, v136 offset:1040
	ds_read_b32 v159, v136 offset:1300
	ds_read_b32 v160, v136 offset:1560
	ds_read_b32 v161, v136 offset:1820
	s_waitcnt lgkmcnt(0)
	v_cvt_pk_bf16_f32 v204, v154, v155
	v_cvt_pk_bf16_f32 v205, v156, v157
	v_cvt_pk_bf16_f32 v206, v158, v159
	v_cvt_pk_bf16_f32 v207, v160, v161
	global_store_dwordx4 v137, v[204:207], s[26:27]
	s_barrier
	s_waitcnt vmcnt(0)
	ds_write_b32 v123, v140 offset:0
	ds_write_b32 v123, v141 offset:4
	ds_write_b32 v123, v142 offset:8
	ds_write_b32 v123, v143 offset:12
	ds_write_b32 v123, v150 offset:8320
	ds_write_b32 v123, v151 offset:8324
	ds_write_b32 v123, v152 offset:8328
	ds_write_b32 v123, v153 offset:8332
	s_waitcnt lgkmcnt(0)
	s_barrier
	s_mov_b64 s[26:27], s[16:17]
	s_add_i32 s4, s2, 896
	s_cmpk_lt_u32 s4, 0x200
	s_cselect_b32 s6, s28, s30
	s_cselect_b32 s7, s29, s31
	s_mov_b32 s16, 0x10500000
	s_cselect_b32 s16, 0x10100000, s16
	s_bfe_u32 s5, s4, 0x10008
	s_lshl_b32 s3, s5, 22
	s_add_u32 s6, s6, s3
	s_addc_u32 s7, s7, 0
	s_lshl_b32 s3, s5, 21
	s_add_i32 s16, s16, s3
	s_and_b32 s3, s4, 15
	s_bfe_u32 s5, s4, 0x40004
	s_lshl_b32 s17, s3, 18
	s_lshl_b32 s20, s5, 8
	s_add_i32 s17, s17, s20
	s_add_u32 s6, s6, s17
	s_addc_u32 s7, s7, 0
	s_add_u32 s12, s6, 0x20000
	s_addc_u32 s13, s7, 0
	s_lshl_b32 s17, s5, 17
	s_lshl_b32 s20, s3, 7
	s_add_i32 s17, s17, s20
	s_add_i32 s16, s16, s17
	s_add_u32 s16, s96, s16
	s_addc_u32 s17, s97, 0
	global_load_dwordx4 v[140:143], v122, s[6:7]
	global_load_dwordx4 v[150:153], v122, s[12:13]
	ds_read_b32 v154, v136 offset:0
	ds_read_b32 v155, v136 offset:260
	ds_read_b32 v156, v136 offset:520
	ds_read_b32 v157, v136 offset:780
	ds_read_b32 v158, v136 offset:1040
	ds_read_b32 v159, v136 offset:1300
	ds_read_b32 v160, v136 offset:1560
	ds_read_b32 v161, v136 offset:1820
	s_waitcnt lgkmcnt(0)
	v_cvt_pk_bf16_f32 v204, v154, v155
	v_cvt_pk_bf16_f32 v205, v156, v157
	v_cvt_pk_bf16_f32 v206, v158, v159
	v_cvt_pk_bf16_f32 v207, v160, v161
	global_store_dwordx4 v137, v[204:207], s[26:27]
	s_barrier
	s_waitcnt vmcnt(0)
	ds_write_b32 v123, v140 offset:0
	ds_write_b32 v123, v141 offset:4
	ds_write_b32 v123, v142 offset:8
	ds_write_b32 v123, v143 offset:12
	ds_write_b32 v123, v150 offset:8320
	ds_write_b32 v123, v151 offset:8324
	ds_write_b32 v123, v152 offset:8328
	ds_write_b32 v123, v153 offset:8332
	s_waitcnt lgkmcnt(0)
	s_barrier
	s_mov_b64 s[26:27], s[16:17]
	ds_read_b32 v154, v136 offset:0
	ds_read_b32 v155, v136 offset:260
	ds_read_b32 v156, v136 offset:520
	ds_read_b32 v157, v136 offset:780
	ds_read_b32 v158, v136 offset:1040
	ds_read_b32 v159, v136 offset:1300
	ds_read_b32 v160, v136 offset:1560
	ds_read_b32 v161, v136 offset:1820
	s_waitcnt lgkmcnt(0)
	v_cvt_pk_bf16_f32 v204, v154, v155
	v_cvt_pk_bf16_f32 v205, v156, v157
	v_cvt_pk_bf16_f32 v206, v158, v159
	v_cvt_pk_bf16_f32 v207, v160, v161
	global_store_dwordx4 v137, v[204:207], s[26:27]
	s_barrier
	v_readlane_b32 s28, v253, 20
	v_readlane_b32 s29, v253, 21
	s_nop 3
	s_add_i32 s4, s2, 1408
	s_and_b32 s3, s4, 15
	s_lshr_b32 s5, s4, 4
	s_mul_i32 s17, s3, 0x220000
	s_lshl_b32 s20, s5, 8
	s_add_i32 s17, s17, s20
	s_add_u32 s6, s28, s17
	s_addc_u32 s7, s29, 0
	s_add_u32 s12, s6, 0x110000
	s_addc_u32 s13, s7, 0
	s_lshl_b32 s17, s5, 17
	s_lshl_b32 s20, s3, 7
	s_add_i32 s17, s17, s20
	s_add_u32 s16, s96, s17
	s_addc_u32 s17, s97, 0
	s_add_u32 s16, s16, 0xf000000
	s_addc_u32 s17, s17, 0
	global_load_dwordx4 v[140:143], v138, s[6:7]
	global_load_dwordx4 v[150:153], v138, s[12:13]
	s_waitcnt vmcnt(0)
	ds_write_b32 v123, v140 offset:0
	ds_write_b32 v123, v141 offset:4
	ds_write_b32 v123, v142 offset:8
	ds_write_b32 v123, v143 offset:12
	ds_write_b32 v123, v150 offset:8320
	ds_write_b32 v123, v151 offset:8324
	ds_write_b32 v123, v152 offset:8328
	ds_write_b32 v123, v153 offset:8332
	s_waitcnt lgkmcnt(0)
	s_barrier
	s_mov_b64 s[26:27], s[16:17]
	s_add_i32 s4, s2, 1536
	s_and_b32 s3, s4, 15
	s_lshr_b32 s5, s4, 4
	s_mul_i32 s17, s3, 0x220000
	s_lshl_b32 s20, s5, 8
	s_add_i32 s17, s17, s20
	s_add_u32 s6, s28, s17
	s_addc_u32 s7, s29, 0
	s_add_u32 s12, s6, 0x110000
	s_addc_u32 s13, s7, 0
	s_lshl_b32 s17, s5, 17
	s_lshl_b32 s20, s3, 7
	s_add_i32 s17, s17, s20
	s_add_u32 s16, s96, s17
	s_addc_u32 s17, s97, 0
	s_add_u32 s16, s16, 0xf000000
	s_addc_u32 s17, s17, 0
	global_load_dwordx4 v[140:143], v138, s[6:7]
	global_load_dwordx4 v[150:153], v138, s[12:13]
	ds_read_b32 v154, v136 offset:0
	ds_read_b32 v155, v136 offset:260
	ds_read_b32 v156, v136 offset:520
	ds_read_b32 v157, v136 offset:780
	ds_read_b32 v158, v136 offset:1040
	ds_read_b32 v159, v136 offset:1300
	ds_read_b32 v160, v136 offset:1560
	ds_read_b32 v161, v136 offset:1820
	s_waitcnt lgkmcnt(0)
	v_mul_f32_e32 v154, v235, v154
	v_mul_f32_e32 v155, v235, v155
	v_mul_f32_e32 v156, v235, v156
	v_mul_f32_e32 v157, v235, v157
	v_mul_f32_e32 v158, v235, v158
	v_mul_f32_e32 v159, v235, v159
	v_mul_f32_e32 v160, v235, v160
	v_mul_f32_e32 v161, v235, v161
	v_cvt_pk_bf16_f32 v204, v154, v155
	v_cvt_pk_bf16_f32 v205, v156, v157
	v_cvt_pk_bf16_f32 v206, v158, v159
	v_cvt_pk_bf16_f32 v207, v160, v161
	global_store_dwordx4 v137, v[204:207], s[26:27]
	s_barrier
	s_waitcnt vmcnt(0)
	ds_write_b32 v123, v140 offset:0
	ds_write_b32 v123, v141 offset:4
	ds_write_b32 v123, v142 offset:8
	ds_write_b32 v123, v143 offset:12
	ds_write_b32 v123, v150 offset:8320
	ds_write_b32 v123, v151 offset:8324
	ds_write_b32 v123, v152 offset:8328
	ds_write_b32 v123, v153 offset:8332
	s_waitcnt lgkmcnt(0)
	s_barrier
	s_mov_b64 s[26:27], s[16:17]
	s_add_i32 s4, s2, 1664
	s_and_b32 s3, s4, 15
	s_lshr_b32 s5, s4, 4
	s_mul_i32 s17, s3, 0x220000
	s_lshl_b32 s20, s5, 8
	s_add_i32 s17, s17, s20
	s_add_u32 s6, s28, s17
	s_addc_u32 s7, s29, 0
	s_add_u32 s12, s6, 0x110000
	s_addc_u32 s13, s7, 0
	s_lshl_b32 s17, s5, 17
	s_lshl_b32 s20, s3, 7
	s_add_i32 s17, s17, s20
	s_add_u32 s16, s96, s17
	s_addc_u32 s17, s97, 0
	s_add_u32 s16, s16, 0xf000000
	s_addc_u32 s17, s17, 0
	global_load_dwordx4 v[140:143], v138, s[6:7]
	global_load_dwordx4 v[150:153], v138, s[12:13]
	ds_read_b32 v154, v136 offset:0
	ds_read_b32 v155, v136 offset:260
	ds_read_b32 v156, v136 offset:520
	ds_read_b32 v157, v136 offset:780
	ds_read_b32 v158, v136 offset:1040
	ds_read_b32 v159, v136 offset:1300
	ds_read_b32 v160, v136 offset:1560
	ds_read_b32 v161, v136 offset:1820
	s_waitcnt lgkmcnt(0)
	v_mul_f32_e32 v154, v235, v154
	v_mul_f32_e32 v155, v235, v155
	v_mul_f32_e32 v156, v235, v156
	v_mul_f32_e32 v157, v235, v157
	v_mul_f32_e32 v158, v235, v158
	v_mul_f32_e32 v159, v235, v159
	v_mul_f32_e32 v160, v235, v160
	v_mul_f32_e32 v161, v235, v161
	v_cvt_pk_bf16_f32 v204, v154, v155
	v_cvt_pk_bf16_f32 v205, v156, v157
	v_cvt_pk_bf16_f32 v206, v158, v159
	v_cvt_pk_bf16_f32 v207, v160, v161
	global_store_dwordx4 v137, v[204:207], s[26:27]
	s_barrier
	s_waitcnt vmcnt(0)
	ds_write_b32 v123, v140 offset:0
	ds_write_b32 v123, v141 offset:4
	ds_write_b32 v123, v142 offset:8
	ds_write_b32 v123, v143 offset:12
	ds_write_b32 v123, v150 offset:8320
	ds_write_b32 v123, v151 offset:8324
	ds_write_b32 v123, v152 offset:8328
	ds_write_b32 v123, v153 offset:8332
	s_waitcnt lgkmcnt(0)
	s_barrier
	s_mov_b64 s[26:27], s[16:17]
	s_add_i32 s4, s2, 1792
	s_and_b32 s3, s4, 15
	s_lshr_b32 s5, s4, 4
	s_mul_i32 s17, s3, 0x220000
	s_lshl_b32 s20, s5, 8
	s_add_i32 s17, s17, s20
	s_add_u32 s6, s28, s17
	s_addc_u32 s7, s29, 0
	s_add_u32 s12, s6, 0x110000
	s_addc_u32 s13, s7, 0
	s_lshl_b32 s17, s5, 17
	s_lshl_b32 s20, s3, 7
	s_add_i32 s17, s17, s20
	s_add_u32 s16, s96, s17
	s_addc_u32 s17, s97, 0
	s_add_u32 s16, s16, 0xf000000
	s_addc_u32 s17, s17, 0
	global_load_dwordx4 v[140:143], v138, s[6:7]
	global_load_dwordx4 v[150:153], v138, s[12:13]
	ds_read_b32 v154, v136 offset:0
	ds_read_b32 v155, v136 offset:260
	ds_read_b32 v156, v136 offset:520
	ds_read_b32 v157, v136 offset:780
	ds_read_b32 v158, v136 offset:1040
	ds_read_b32 v159, v136 offset:1300
	ds_read_b32 v160, v136 offset:1560
	ds_read_b32 v161, v136 offset:1820
	s_waitcnt lgkmcnt(0)
	v_mul_f32_e32 v154, v235, v154
	v_mul_f32_e32 v155, v235, v155
	v_mul_f32_e32 v156, v235, v156
	v_mul_f32_e32 v157, v235, v157
	v_mul_f32_e32 v158, v235, v158
	v_mul_f32_e32 v159, v235, v159
	v_mul_f32_e32 v160, v235, v160
	v_mul_f32_e32 v161, v235, v161
	v_cvt_pk_bf16_f32 v204, v154, v155
	v_cvt_pk_bf16_f32 v205, v156, v157
	v_cvt_pk_bf16_f32 v206, v158, v159
	v_cvt_pk_bf16_f32 v207, v160, v161
	global_store_dwordx4 v137, v[204:207], s[26:27]
	s_barrier
	s_waitcnt vmcnt(0)
	ds_write_b32 v123, v140 offset:0
	ds_write_b32 v123, v141 offset:4
	ds_write_b32 v123, v142 offset:8
	ds_write_b32 v123, v143 offset:12
	ds_write_b32 v123, v150 offset:8320
	ds_write_b32 v123, v151 offset:8324
	ds_write_b32 v123, v152 offset:8328
	ds_write_b32 v123, v153 offset:8332
	s_waitcnt lgkmcnt(0)
	s_barrier
	s_mov_b64 s[26:27], s[16:17]
	s_add_i32 s4, s2, 1920
	s_and_b32 s3, s4, 15
	s_lshr_b32 s5, s4, 4
	s_mul_i32 s17, s3, 0x220000
	s_lshl_b32 s20, s5, 8
	s_add_i32 s17, s17, s20
	s_add_u32 s6, s28, s17
	s_addc_u32 s7, s29, 0
	s_add_u32 s12, s6, 0x110000
	s_addc_u32 s13, s7, 0
	s_lshl_b32 s17, s5, 17
	s_lshl_b32 s20, s3, 7
	s_add_i32 s17, s17, s20
	s_add_u32 s16, s96, s17
	s_addc_u32 s17, s97, 0
	s_add_u32 s16, s16, 0xf000000
	s_addc_u32 s17, s17, 0
	global_load_dwordx4 v[140:143], v138, s[6:7]
	global_load_dwordx4 v[150:153], v138, s[12:13]
	ds_read_b32 v154, v136 offset:0
	ds_read_b32 v155, v136 offset:260
	ds_read_b32 v156, v136 offset:520
	ds_read_b32 v157, v136 offset:780
	ds_read_b32 v158, v136 offset:1040
	ds_read_b32 v159, v136 offset:1300
	ds_read_b32 v160, v136 offset:1560
	ds_read_b32 v161, v136 offset:1820
	s_waitcnt lgkmcnt(0)
	v_mul_f32_e32 v154, v235, v154
	v_mul_f32_e32 v155, v235, v155
	v_mul_f32_e32 v156, v235, v156
	v_mul_f32_e32 v157, v235, v157
	v_mul_f32_e32 v158, v235, v158
	v_mul_f32_e32 v159, v235, v159
	v_mul_f32_e32 v160, v235, v160
	v_mul_f32_e32 v161, v235, v161
	v_cvt_pk_bf16_f32 v204, v154, v155
	v_cvt_pk_bf16_f32 v205, v156, v157
	v_cvt_pk_bf16_f32 v206, v158, v159
	v_cvt_pk_bf16_f32 v207, v160, v161
	global_store_dwordx4 v137, v[204:207], s[26:27]
	s_barrier
	s_waitcnt vmcnt(0)
	ds_write_b32 v123, v140 offset:0
	ds_write_b32 v123, v141 offset:4
	ds_write_b32 v123, v142 offset:8
	ds_write_b32 v123, v143 offset:12
	ds_write_b32 v123, v150 offset:8320
	ds_write_b32 v123, v151 offset:8324
	ds_write_b32 v123, v152 offset:8328
	ds_write_b32 v123, v153 offset:8332
	s_waitcnt lgkmcnt(0)
	s_barrier
	s_mov_b64 s[26:27], s[16:17]
	s_add_i32 s4, s2, 2048
	s_and_b32 s3, s4, 15
	s_lshr_b32 s5, s4, 4
	s_mul_i32 s17, s3, 0x220000
	s_lshl_b32 s20, s5, 8
	s_add_i32 s17, s17, s20
	s_add_u32 s6, s28, s17
	s_addc_u32 s7, s29, 0
	s_add_u32 s12, s6, 0x110000
	s_addc_u32 s13, s7, 0
	s_lshl_b32 s17, s5, 17
	s_lshl_b32 s20, s3, 7
	s_add_i32 s17, s17, s20
	s_add_u32 s16, s96, s17
	s_addc_u32 s17, s97, 0
	s_add_u32 s16, s16, 0xf000000
	s_addc_u32 s17, s17, 0
	global_load_dwordx4 v[140:143], v138, s[6:7]
	global_load_dwordx4 v[150:153], v138, s[12:13]
	ds_read_b32 v154, v136 offset:0
	ds_read_b32 v155, v136 offset:260
	ds_read_b32 v156, v136 offset:520
	ds_read_b32 v157, v136 offset:780
	ds_read_b32 v158, v136 offset:1040
	ds_read_b32 v159, v136 offset:1300
	ds_read_b32 v160, v136 offset:1560
	ds_read_b32 v161, v136 offset:1820
	s_waitcnt lgkmcnt(0)
	v_mul_f32_e32 v154, v235, v154
	v_mul_f32_e32 v155, v235, v155
	v_mul_f32_e32 v156, v235, v156
	v_mul_f32_e32 v157, v235, v157
	v_mul_f32_e32 v158, v235, v158
	v_mul_f32_e32 v159, v235, v159
	v_mul_f32_e32 v160, v235, v160
	v_mul_f32_e32 v161, v235, v161
	v_cvt_pk_bf16_f32 v204, v154, v155
	v_cvt_pk_bf16_f32 v205, v156, v157
	v_cvt_pk_bf16_f32 v206, v158, v159
	v_cvt_pk_bf16_f32 v207, v160, v161
	global_store_dwordx4 v137, v[204:207], s[26:27]
	s_barrier
	s_waitcnt vmcnt(0)
	ds_write_b32 v123, v140 offset:0
	ds_write_b32 v123, v141 offset:4
	ds_write_b32 v123, v142 offset:8
	ds_write_b32 v123, v143 offset:12
	ds_write_b32 v123, v150 offset:8320
	ds_write_b32 v123, v151 offset:8324
	ds_write_b32 v123, v152 offset:8328
	ds_write_b32 v123, v153 offset:8332
	s_waitcnt lgkmcnt(0)
	s_barrier
	s_mov_b64 s[26:27], s[16:17]
	ds_read_b32 v154, v136 offset:0
	ds_read_b32 v155, v136 offset:260
	ds_read_b32 v156, v136 offset:520
	ds_read_b32 v157, v136 offset:780
	ds_read_b32 v158, v136 offset:1040
	ds_read_b32 v159, v136 offset:1300
	ds_read_b32 v160, v136 offset:1560
	ds_read_b32 v161, v136 offset:1820
	s_waitcnt lgkmcnt(0)
	v_mul_f32_e32 v154, v235, v154
	v_mul_f32_e32 v155, v235, v155
	v_mul_f32_e32 v156, v235, v156
	v_mul_f32_e32 v157, v235, v157
	v_mul_f32_e32 v158, v235, v158
	v_mul_f32_e32 v159, v235, v159
	v_mul_f32_e32 v160, v235, v160
	v_mul_f32_e32 v161, v235, v161
	v_cvt_pk_bf16_f32 v204, v154, v155
	v_cvt_pk_bf16_f32 v205, v156, v157
	v_cvt_pk_bf16_f32 v206, v158, v159
	v_cvt_pk_bf16_f32 v207, v160, v161
	global_store_dwordx4 v137, v[204:207], s[26:27]
	s_barrier
	s_branch .LBB0_243
